# nt hint also on the x f32 loads of the input-conversion phase
# speedup vs baseline: 1.0072x; 1.0028x over previous
; #define LAS __attribute__((address_space(3)))
; __device__ __forceinline__ void conv_load(const ConvDesc& d, f32x4 (&v)[16], int lane) {
;     const int kq = lane >> 4, n4 = (lane & 15) * 4;
;     const float* src = d.src + (size_t)(2 * kq) * d.Nsrc + n4;
; #pragma unroll
;     for (int i = 0; i < 8; ++i) { v[2 * i] = __builtin_nontemporal_load((const f32x4*)(src + (size_t)(8 * i) * d.Nsrc)); v[2 * i + 1] = __builtin_nontemporal_load((const f32x4*)(src + (size_t)(8 * i + 1) * d.Nsrc)); }
; }
; __device__ __forceinline__ void conv_scatter(const ConvDesc& d, f32x4 (&v)[16], LAS unsigned* scr, int lane) {
;     const int kq = lane >> 4, n4 = (lane & 15) * 4;
;     if (d.g) {
; #pragma unroll
;         for (int i = 0; i < 8; ++i) { const f32x2 gg = *(const f32x2*)(d.g + 8 * i + 2 * kq); v[2 * i] = v[2 * i] * gg.x; v[2 * i + 1] = v[2 * i + 1] * gg.y; } }
.LBB0_57:
	s_lshl_b32 s4, s4, 6
	s_lshl_b32 s13, s13, 9
	s_and_b32 s4, s4, 0x1c0
	s_or_b32 s82, s13, s4
	s_ashr_i32 s83, s82, 31
	s_mul_i32 s4, s72, s83
	s_mul_hi_u32 s13, s72, s82
	s_add_i32 s4, s13, s4
	s_mul_i32 s13, s73, s82
	s_add_i32 s35, s4, s13
	s_mul_i32 s34, s72, s82
	s_lshl_b64 s[34:35], s[34:35], 2
	s_add_u32 s4, s70, s34
	s_addc_u32 s13, s71, s35
	s_lshl_b64 s[34:35], s[86:87], 2
	s_add_u32 s4, s4, s34
	s_addc_u32 s15, s13, s35
	s_ashr_i32 s13, s12, 31
	s_lshl_b64 s[12:13], s[12:13], 2
	s_add_u32 s12, s4, s12
	v_mul_u32_u24_e32 v0, s72, v73
	s_addc_u32 s13, s15, s13
	v_lshlrev_b32_e32 v66, 2, v0
	v_lshl_add_u64 v[0:1], s[12:13], 0, v[66:67]
	v_lshl_add_u64 v[0:1], v[0:1], 0, v[68:69]
	s_lshl_b64 s[12:13], s[72:73], 2
	v_lshl_add_u64 v[2:3], v[0:1], 0, s[12:13]
	s_mul_i32 s4, s72, 28
	global_load_dwordx4 v[40:43], v[0:1], off nt
	global_load_dwordx4 v[52:55], v[2:3], off nt
	v_lshl_add_u64 v[0:1], v[2:3], 0, s[4:5]
	v_lshl_add_u64 v[2:3], v[0:1], 0, s[12:13]
	global_load_dwordx4 v[48:51], v[0:1], off nt
	global_load_dwordx4 v[60:63], v[2:3], off nt
	v_lshl_add_u64 v[0:1], v[2:3], 0, s[4:5]
	v_lshl_add_u64 v[2:3], v[0:1], 0, s[12:13]
	global_load_dwordx4 v[44:47], v[0:1], off nt
	global_load_dwordx4 v[56:59], v[2:3], off nt
	v_lshl_add_u64 v[0:1], v[2:3], 0, s[4:5]
	global_load_dwordx4 v[28:31], v[0:1], off nt
	v_lshl_add_u64 v[0:1], v[0:1], 0, s[12:13]
	global_load_dwordx4 v[36:39], v[0:1], off nt
	v_lshl_add_u64 v[0:1], v[0:1], 0, s[4:5]
	global_load_dwordx4 v[24:27], v[0:1], off nt
	v_lshl_add_u64 v[0:1], v[0:1], 0, s[12:13]
	global_load_dwordx4 v[32:35], v[0:1], off nt
	v_lshl_add_u64 v[0:1], v[0:1], 0, s[4:5]
	global_load_dwordx4 v[12:15], v[0:1], off nt
	v_lshl_add_u64 v[0:1], v[0:1], 0, s[12:13]
	global_load_dwordx4 v[20:23], v[0:1], off nt
	v_lshl_add_u64 v[0:1], v[0:1], 0, s[4:5]
	global_load_dwordx4 v[4:7], v[0:1], off nt
	v_lshl_add_u64 v[0:1], v[0:1], 0, s[12:13]
	v_lshl_add_u64 v[8:9], v[0:1], 0, s[4:5]
	global_load_dwordx4 v[16:19], v[0:1], off nt
	s_cmp_eq_u64 s[68:69], 0
	global_load_dwordx4 v[0:3], v[8:9], off nt
	v_lshl_add_u64 v[8:9], v[8:9], 0, s[12:13]
	global_load_dwordx4 v[8:11], v[8:9], off nt
	s_cbranch_scc1 .LBB0_19
	s_lshl_b64 s[12:13], s[82:83], 2
	s_add_u32 s68, s68, s12
	s_addc_u32 s69, s69, s13
	global_load_dwordx2 v[84:85], v81, s[68:69] nt
	global_load_dwordx2 v[86:87], v81, s[68:69] offset:32 nt
	global_load_dwordx2 v[88:89], v81, s[68:69] offset:64 nt
	global_load_dwordx2 v[90:91], v81, s[68:69] offset:96 nt
	global_load_dwordx2 v[92:93], v81, s[68:69] offset:128 nt
	global_load_dwordx2 v[94:95], v81, s[68:69] offset:160 nt
	global_load_dwordx2 v[96:97], v81, s[68:69] offset:192 nt
	global_load_dwordx2 v[98:99], v81, s[68:69] offset:224 nt
	s_waitcnt vmcnt(7)
	v_pk_mul_f32 v[42:43], v[42:43], v[84:85] op_sel_hi:[1,0]
	v_pk_mul_f32 v[40:41], v[40:41], v[84:85] op_sel_hi:[1,0]
	v_pk_mul_f32 v[54:55], v[54:55], v[84:85] op_sel:[0,1]
	v_pk_mul_f32 v[52:53], v[52:53], v[84:85] op_sel:[0,1]
	s_waitcnt vmcnt(6)
	v_pk_mul_f32 v[50:51], v[50:51], v[86:87] op_sel_hi:[1,0]
	v_pk_mul_f32 v[48:49], v[48:49], v[86:87] op_sel_hi:[1,0]
	v_pk_mul_f32 v[62:63], v[62:63], v[86:87] op_sel:[0,1]
	v_pk_mul_f32 v[60:61], v[60:61], v[86:87] op_sel:[0,1]
	s_waitcnt vmcnt(5)
	v_pk_mul_f32 v[46:47], v[46:47], v[88:89] op_sel_hi:[1,0]
	v_pk_mul_f32 v[44:45], v[44:45], v[88:89] op_sel_hi:[1,0]
	v_pk_mul_f32 v[58:59], v[58:59], v[88:89] op_sel:[0,1]
	v_pk_mul_f32 v[56:57], v[56:57], v[88:89] op_sel:[0,1]
	s_waitcnt vmcnt(4)
	v_pk_mul_f32 v[30:31], v[30:31], v[90:91] op_sel_hi:[1,0]
	v_pk_mul_f32 v[28:29], v[28:29], v[90:91] op_sel_hi:[1,0]
	v_pk_mul_f32 v[38:39], v[38:39], v[90:91] op_sel:[0,1]
	v_pk_mul_f32 v[36:37], v[36:37], v[90:91] op_sel:[0,1]
	s_waitcnt vmcnt(3)
	v_pk_mul_f32 v[26:27], v[26:27], v[92:93] op_sel_hi:[1,0]
	v_pk_mul_f32 v[24:25], v[24:25], v[92:93] op_sel_hi:[1,0]
	v_pk_mul_f32 v[34:35], v[34:35], v[92:93] op_sel:[0,1]
	v_pk_mul_f32 v[32:33], v[32:33], v[92:93] op_sel:[0,1]
	s_waitcnt vmcnt(2)
	v_pk_mul_f32 v[14:15], v[14:15], v[94:95] op_sel_hi:[1,0]
	v_pk_mul_f32 v[12:13], v[12:13], v[94:95] op_sel_hi:[1,0]
	v_pk_mul_f32 v[22:23], v[22:23], v[94:95] op_sel:[0,1]
	v_pk_mul_f32 v[20:21], v[20:21], v[94:95] op_sel:[0,1]
	s_waitcnt vmcnt(1)
	v_pk_mul_f32 v[6:7], v[6:7], v[96:97] op_sel_hi:[1,0]
	v_pk_mul_f32 v[4:5], v[4:5], v[96:97] op_sel_hi:[1,0]
	v_pk_mul_f32 v[18:19], v[18:19], v[96:97] op_sel:[0,1]
	v_pk_mul_f32 v[16:17], v[16:17], v[96:97] op_sel:[0,1]
	s_waitcnt vmcnt(0)
	v_pk_mul_f32 v[2:3], v[2:3], v[98:99] op_sel_hi:[1,0]
	v_pk_mul_f32 v[0:1], v[0:1], v[98:99] op_sel_hi:[1,0]
	v_pk_mul_f32 v[10:11], v[10:11], v[98:99] op_sel:[0,1]
	v_pk_mul_f32 v[8:9], v[8:9], v[98:99] op_sel:[0,1]
	s_branch .LBB0_19
